# grid barriers B3-B6: non-leader workgroups poll the global generation word directly instead of the per-XCD relay word (one hop fewer)
# speedup vs baseline: 1.0058x; 1.0002x over previous
.LBB0_724:
	s_or_b64 exec, exec, s[4:5]
	v_cvt_f32_u32_e32 v5, v3
	s_waitcnt vmcnt(0)
	v_readfirstlane_b32 s4, v4
	v_sub_u32_e32 v4, 0, v3
	v_rcp_iflag_f32_e32 v5, v5
	v_add_u32_e32 v6, s4, v1
	v_mul_f32_e32 v5, 0x4f7ffffe, v5
	v_cvt_u32_f32_e32 v5, v5
	v_mul_lo_u32 v1, v4, v5
	v_mul_hi_u32 v1, v5, v1
	v_add_u32_e32 v1, v5, v1
	v_mul_hi_u32 v1, v6, v1
	v_mul_lo_u32 v4, v1, v3
	v_sub_u32_e32 v4, v6, v4
	v_add_u32_e32 v5, 1, v1
	v_cmp_ge_u32_e32 vcc, v4, v3
	s_nop 1
	v_cndmask_b32_e32 v1, v1, v5, vcc
	v_sub_u32_e32 v5, v4, v3
	v_cndmask_b32_e32 v4, v4, v5, vcc
	v_add_u32_e32 v5, 1, v1
	v_cmp_ge_u32_e32 vcc, v4, v3
	v_add_u32_e32 v4, 1, v6
	s_nop 0
	v_cndmask_b32_e32 v1, v1, v5, vcc
	v_mul_lo_u32 v5, v3, v1
	v_add_u32_e32 v3, v5, v3
	v_cmp_ne_u32_e32 vcc, v4, v3
	s_and_saveexec_b64 s[4:5], vcc
	s_xor_b64 s[4:5], exec, s[4:5]
	s_cbranch_execz .LBB0_738
	s_waitcnt lgkmcnt(0)
	v_mov_b32_e32 v2, 0
	global_load_dword v3, v2, s[76:77] sc1
	s_waitcnt vmcnt(0)
	v_cmp_eq_u32_e32 vcc, v3, v1
	s_and_saveexec_b64 s[6:7], vcc
	s_cbranch_execz .LBB0_737
	s_mov_b32 s18, 1
	s_mov_b64 s[8:9], 0
	s_branch .LBB0_728

.LBB0_732:
	global_load_dword v3, v2, s[76:77] sc1
	s_add_i32 s18, s18, 1
	s_mov_b64 s[14:15], -1
	s_waitcnt vmcnt(0)
	v_cmp_ne_u32_e32 vcc, v3, v1
	s_orn2_b64 s[12:13], vcc, exec
	s_branch .LBB0_727

.LBB0_1081:
	s_or_b64 exec, exec, s[4:5]
	v_cvt_f32_u32_e32 v5, v3
	s_waitcnt vmcnt(0)
	v_readfirstlane_b32 s4, v4
	v_sub_u32_e32 v4, 0, v3
	v_rcp_iflag_f32_e32 v5, v5
	v_add_u32_e32 v6, s4, v1
	v_mul_f32_e32 v5, 0x4f7ffffe, v5
	v_cvt_u32_f32_e32 v5, v5
	v_mul_lo_u32 v1, v4, v5
	v_mul_hi_u32 v1, v5, v1
	v_add_u32_e32 v1, v5, v1
	v_mul_hi_u32 v1, v6, v1
	v_mul_lo_u32 v4, v1, v3
	v_sub_u32_e32 v4, v6, v4
	v_add_u32_e32 v5, 1, v1
	v_cmp_ge_u32_e32 vcc, v4, v3
	s_nop 1
	v_cndmask_b32_e32 v1, v1, v5, vcc
	v_sub_u32_e32 v5, v4, v3
	v_cndmask_b32_e32 v4, v4, v5, vcc
	v_add_u32_e32 v5, 1, v1
	v_cmp_ge_u32_e32 vcc, v4, v3
	v_add_u32_e32 v4, 1, v6
	s_nop 0
	v_cndmask_b32_e32 v1, v1, v5, vcc
	v_mul_lo_u32 v5, v3, v1
	v_add_u32_e32 v3, v5, v3
	v_cmp_ne_u32_e32 vcc, v4, v3
	s_and_saveexec_b64 s[4:5], vcc
	s_xor_b64 s[4:5], exec, s[4:5]
	s_cbranch_execz .LBB0_1095
	s_waitcnt lgkmcnt(0)
	v_mov_b32_e32 v2, 0
	global_load_dword v3, v2, s[76:77] sc1
	s_waitcnt vmcnt(0)
	v_cmp_eq_u32_e32 vcc, v3, v1
	s_and_saveexec_b64 s[8:9], vcc
	s_cbranch_execz .LBB0_1094
	s_mov_b32 s20, 1
	s_mov_b64 s[10:11], 0
	s_branch .LBB0_1085

.LBB0_1089:
	global_load_dword v3, v2, s[76:77] sc1
	s_add_i32 s20, s20, 1
	s_mov_b64 s[16:17], -1
	s_waitcnt vmcnt(0)
	v_cmp_ne_u32_e32 vcc, v3, v1
	s_orn2_b64 s[14:15], vcc, exec
	s_branch .LBB0_1084
